# grid barrier: acquire invalidate issued right after the arrival store so it overlaps the polling
# baseline (speedup 1.0000x reference)
; #define FB_LD(p) __hip_atomic_load((p), __ATOMIC_RELAXED, __HIP_MEMORY_SCOPE_AGENT)
; #define FB_ST(p, v) __hip_atomic_store((p), (v), __ATOMIC_RELAXED, __HIP_MEMORY_SCOPE_AGENT)
; __device__ __forceinline__ void flag_barrier(unsigned* base, unsigned gen) {
;     ...
;         __builtin_amdgcn_fence(__ATOMIC_RELEASE, "agent");
;         asm volatile("s_waitcnt vmcnt(0)" ::: "memory");
;         if (lane == 0) FB_ST(base + 64 * (1 + c), gen);
;         if (c == 0) {
;             unsigned sp = 0;
;             for (;;) {
;                 unsigned ok = 1u;
;                 for (int m = lane; m < G; m += 64) ok &= (unsigned)(FB_LD(base + 64 * (1 + m)) >= gen);
;                 if (__all((int)ok)) break;
;                 __builtin_amdgcn_s_sleep(1); if (++sp > (1u << 22)) break;
;             }
;             if (lane == 0) FB_ST(base, gen);
;         }
;         { unsigned sp = 0; while (FB_LD(base) < gen) { __builtin_amdgcn_s_sleep(1); if (++sp > (1u << 22)) break; } }
;         __builtin_amdgcn_fence(__ATOMIC_ACQUIRE, "agent");
.LBB0_501:
	s_or_b64 exec, exec, s[8:9]
	buffer_inv sc1
	s_andn2_b64 vcc, exec, s[94:95]
	s_cbranch_vccnz .LBB0_513
	v_cmp_gt_i32_e64 s[8:9], s5, v163
	s_mov_b32 s6, 0
	s_branch .LBB0_504

; #define FB_LD(p) __hip_atomic_load((p), __ATOMIC_RELAXED, __HIP_MEMORY_SCOPE_AGENT)
; __device__ __forceinline__ void flag_barrier(unsigned* base, unsigned gen) {
;     ...
;         { unsigned sp = 0; while (FB_LD(base) < gen) { __builtin_amdgcn_s_sleep(1); if (++sp > (1u << 22)) break; } }
;         __builtin_amdgcn_fence(__ATOMIC_ACQUIRE, "agent");
;         asm volatile("s_waitcnt vmcnt(0)" ::: "memory");
;     }
;     __syncthreads();
.LBB0_515:
	global_load_dword v0, v145, s[12:13] sc1
	s_mov_b64 s[8:9], -1
	s_waitcnt vmcnt(0)
	v_cmp_le_u32_e32 vcc, s4, v0
	s_cbranch_vccnz .LBB0_514
	s_sleep 1
	global_load_dword v0, v145, s[12:13] sc1
	s_waitcnt vmcnt(0)
	v_cmp_gt_u32_e32 vcc, s4, v0
	s_cbranch_vccz .LBB0_514
	s_sleep 1
	global_load_dword v0, v145, s[12:13] sc1
	s_waitcnt vmcnt(0)
	v_cmp_gt_u32_e32 vcc, s4, v0
	s_cbranch_vccz .LBB0_514
	s_sleep 1
	global_load_dword v0, v145, s[12:13] sc1
	s_waitcnt vmcnt(0)
	v_cmp_gt_u32_e32 vcc, s4, v0
	s_cbranch_vccz .LBB0_514
	s_sleep 1
	global_load_dword v0, v145, s[12:13] sc1
	s_waitcnt vmcnt(0)
	v_cmp_gt_u32_e32 vcc, s4, v0
	s_cbranch_vccz .LBB0_514
	s_add_i32 s5, s5, -5
	s_cmp_eq_u32 s5, 0
	s_cselect_b64 s[8:9], -1, 0
	s_sleep 1
	s_branch .LBB0_514
.LBB0_521:
	s_waitcnt vmcnt(0)
.LBB0_522:
	s_or_b64 exec, exec, s[10:11]
	s_mov_b64 s[8:9], 0
	s_barrier
